# GEMM k-loop: next-tile global loads + address adds interleaved between MFMA pairs (only 2 loads before the MFMAs); SSD conv item: token loads batched 16 at a time
# speedup vs baseline: 1.0677x; 1.0335x over previous
; DI bfr f2bf(float a) { return (bfr)(pk2(a, 0.f) & 0xffffu); }
; DI float bf2f(bfr x) { return __uint_as_float(((unsigned)x) << 16); }
; DI float siluf_(float x) { return x / (1.f + __expf(-x)); }
; DI void ssd_conv_phase(const Params& p, int ei, unsigned char* smem) {
;     ...
;       for (int k = 0; k < 32; ++k) {
;         const float r3 = bf2f(xraw[(tg0 + k) * 1024 + c]);
;         const float y = siluf_(bias + w0 * r0 + w1 * r1 + w2 * r2 + w3 * r3);
;         r0 = r1; r1 = r2; r2 = r3;
;         const bfr yb = f2bf(y);
;         if (slab >= 8) bct[(tg0 + k) * 512 + c - 512] = yb;
;         if (slab < 12) tile[lane * 136 + tq * 32 + k] = yb;
;       }
.LBB0_585:
	v_lshl_add_u64 v[56:57], v[42:43], 0, v[176:177]
	v_lshl_add_u64 v[58:59], v[38:39], 0, v[176:177]
	v_lshl_add_u64 v[60:61], v[40:41], 0, v[176:177]
	v_lshl_add_u64 v[62:63], v[36:37], 0, v[176:177]
	v_mov_b32_e32 v64, v1
	s_mov_b32 s34, 0
.Lconv_round:
	global_load_ushort v66, v[56:57], off
	global_load_ushort v67, v[58:59], off
	v_lshl_add_u64 v[56:57], v[56:57], 0, s[78:79]
	v_lshl_add_u64 v[58:59], v[58:59], 0, s[78:79]
	global_load_ushort v68, v[56:57], off
	global_load_ushort v69, v[58:59], off
	v_lshl_add_u64 v[56:57], v[56:57], 0, s[78:79]
	v_lshl_add_u64 v[58:59], v[58:59], 0, s[78:79]
	global_load_ushort v70, v[56:57], off
	global_load_ushort v71, v[58:59], off
	v_lshl_add_u64 v[56:57], v[56:57], 0, s[78:79]
	v_lshl_add_u64 v[58:59], v[58:59], 0, s[78:79]
	global_load_ushort v72, v[56:57], off
	global_load_ushort v73, v[58:59], off
	v_lshl_add_u64 v[56:57], v[56:57], 0, s[78:79]
	v_lshl_add_u64 v[58:59], v[58:59], 0, s[78:79]
	global_load_ushort v74, v[56:57], off
	global_load_ushort v75, v[58:59], off
	v_lshl_add_u64 v[56:57], v[56:57], 0, s[78:79]
	v_lshl_add_u64 v[58:59], v[58:59], 0, s[78:79]
	global_load_ushort v76, v[56:57], off
	global_load_ushort v77, v[58:59], off
	v_lshl_add_u64 v[56:57], v[56:57], 0, s[78:79]
	v_lshl_add_u64 v[58:59], v[58:59], 0, s[78:79]
	global_load_ushort v78, v[56:57], off
	global_load_ushort v79, v[58:59], off
	v_lshl_add_u64 v[56:57], v[56:57], 0, s[78:79]
	v_lshl_add_u64 v[58:59], v[58:59], 0, s[78:79]
	global_load_ushort v80, v[56:57], off
	global_load_ushort v81, v[58:59], off
	v_lshl_add_u64 v[56:57], v[56:57], 0, s[78:79]
	v_lshl_add_u64 v[58:59], v[58:59], 0, s[78:79]
	s_waitcnt vmcnt(0)
	v_lshlrev_b32_e32 v66, 16, v66
	v_lshlrev_b32_e32 v67, 16, v67
	v_lshlrev_b32_e32 v68, 16, v68
	v_lshlrev_b32_e32 v69, 16, v69
	v_lshlrev_b32_e32 v70, 16, v70
	v_lshlrev_b32_e32 v71, 16, v71
	v_lshlrev_b32_e32 v72, 16, v72
	v_lshlrev_b32_e32 v73, 16, v73
	v_lshlrev_b32_e32 v74, 16, v74
	v_lshlrev_b32_e32 v75, 16, v75
	v_lshlrev_b32_e32 v76, 16, v76
	v_lshlrev_b32_e32 v77, 16, v77
	v_lshlrev_b32_e32 v78, 16, v78
	v_lshlrev_b32_e32 v79, 16, v79
	v_lshlrev_b32_e32 v80, 16, v80
	v_lshlrev_b32_e32 v81, 16, v81
	v_fma_f32 v130, v46, v54, v49
	v_fmac_f32_e32 v130, v47, v52
	v_fmac_f32_e32 v130, v48, v51
	v_fmac_f32_e32 v130, v50, v66
	v_mul_f32_e32 v131, 0xbfb8aa3b, v130
	v_exp_f32_e32 v131, v131
	s_nop 0
	v_add_f32_e32 v131, 1.0, v131
	v_div_scale_f32 v132, s[54:55], v131, v131, v130
	v_rcp_f32_e32 v133, v132
	s_nop 0
	v_fma_f32 v134, -v132, v133, 1.0
	v_fmac_f32_e32 v133, v134, v133
	v_div_scale_f32 v134, vcc, v130, v131, v130
	v_mul_f32_e32 v135, v134, v133
	v_fma_f32 v136, -v132, v135, v134
	v_fmac_f32_e32 v135, v136, v133
	v_fma_f32 v132, -v132, v135, v134
	v_div_fmas_f32 v132, v132, v133, v135
	v_div_fixup_f32 v130, v132, v131, v130
	v_cvt_pk_bf16_f32 v98, v130, s0
	v_fma_f32 v130, v46, v52, v49
	v_fmac_f32_e32 v130, v47, v51
	v_fmac_f32_e32 v130, v48, v66
	v_fmac_f32_e32 v130, v50, v67
	v_mul_f32_e32 v131, 0xbfb8aa3b, v130
	v_exp_f32_e32 v131, v131
	s_nop 0
	v_add_f32_e32 v131, 1.0, v131
	v_div_scale_f32 v132, s[54:55], v131, v131, v130
	v_rcp_f32_e32 v133, v132
	s_nop 0
	v_fma_f32 v134, -v132, v133, 1.0
	v_fmac_f32_e32 v133, v134, v133
	v_div_scale_f32 v134, vcc, v130, v131, v130
	v_mul_f32_e32 v135, v134, v133
	v_fma_f32 v136, -v132, v135, v134
	v_fmac_f32_e32 v135, v136, v133
	v_fma_f32 v132, -v132, v135, v134
	v_div_fmas_f32 v132, v132, v133, v135
	v_div_fixup_f32 v130, v132, v131, v130
	v_cvt_pk_bf16_f32 v99, v130, s0
	v_fma_f32 v130, v46, v51, v49
	v_fmac_f32_e32 v130, v47, v66
	v_fmac_f32_e32 v130, v48, v67
	v_fmac_f32_e32 v130, v50, v68
	v_mul_f32_e32 v131, 0xbfb8aa3b, v130
	v_exp_f32_e32 v131, v131
	s_nop 0
	v_add_f32_e32 v131, 1.0, v131
	v_div_scale_f32 v132, s[54:55], v131, v131, v130
	v_rcp_f32_e32 v133, v132
	s_nop 0
	v_fma_f32 v134, -v132, v133, 1.0
	v_fmac_f32_e32 v133, v134, v133
	v_div_scale_f32 v134, vcc, v130, v131, v130
	v_mul_f32_e32 v135, v134, v133
	v_fma_f32 v136, -v132, v135, v134
	v_fmac_f32_e32 v135, v136, v133
	v_fma_f32 v132, -v132, v135, v134
	v_div_fmas_f32 v132, v132, v133, v135
	v_div_fixup_f32 v130, v132, v131, v130
	v_cvt_pk_bf16_f32 v100, v130, s0
	v_fma_f32 v130, v46, v66, v49
	v_fmac_f32_e32 v130, v47, v67
	v_fmac_f32_e32 v130, v48, v68
	v_fmac_f32_e32 v130, v50, v69
	v_mul_f32_e32 v131, 0xbfb8aa3b, v130
	v_exp_f32_e32 v131, v131
	s_nop 0
	v_add_f32_e32 v131, 1.0, v131
	v_div_scale_f32 v132, s[54:55], v131, v131, v130
	v_rcp_f32_e32 v133, v132
	s_nop 0
	v_fma_f32 v134, -v132, v133, 1.0
	v_fmac_f32_e32 v133, v134, v133
	v_div_scale_f32 v134, vcc, v130, v131, v130
	v_mul_f32_e32 v135, v134, v133
	v_fma_f32 v136, -v132, v135, v134
	v_fmac_f32_e32 v135, v136, v133
	v_fma_f32 v132, -v132, v135, v134
	v_div_fmas_f32 v132, v132, v133, v135
	v_div_fixup_f32 v130, v132, v131, v130
	v_cvt_pk_bf16_f32 v101, v130, s0
	v_fma_f32 v130, v46, v67, v49
	v_fmac_f32_e32 v130, v47, v68
	v_fmac_f32_e32 v130, v48, v69
	v_fmac_f32_e32 v130, v50, v70
	v_mul_f32_e32 v131, 0xbfb8aa3b, v130
	v_exp_f32_e32 v131, v131
	s_nop 0
	v_add_f32_e32 v131, 1.0, v131
	v_div_scale_f32 v132, s[54:55], v131, v131, v130
	v_rcp_f32_e32 v133, v132
	s_nop 0
	v_fma_f32 v134, -v132, v133, 1.0
	v_fmac_f32_e32 v133, v134, v133
	v_div_scale_f32 v134, vcc, v130, v131, v130
	v_mul_f32_e32 v135, v134, v133
	v_fma_f32 v136, -v132, v135, v134
	v_fmac_f32_e32 v135, v136, v133
	v_fma_f32 v132, -v132, v135, v134
	v_div_fmas_f32 v132, v132, v133, v135
	v_div_fixup_f32 v130, v132, v131, v130
	v_cvt_pk_bf16_f32 v102, v130, s0
	v_fma_f32 v130, v46, v68, v49
	v_fmac_f32_e32 v130, v47, v69
	v_fmac_f32_e32 v130, v48, v70
; DI bfr f2bf(float a) { return (bfr)(pk2(a, 0.f) & 0xffffu); }
; DI float bf2f(bfr x) { return __uint_as_float(((unsigned)x) << 16); }
; DI float siluf_(float x) { return x / (1.f + __expf(-x)); }
; DI void ssd_conv_phase(const Params& p, int ei, unsigned char* smem) {
;     ...
;       for (int k = 0; k < 32; ++k) {
;         const float r3 = bf2f(xraw[(tg0 + k) * 1024 + c]);
;         const float y = siluf_(bias + w0 * r0 + w1 * r1 + w2 * r2 + w3 * r3);
;         r0 = r1; r1 = r2; r2 = r3;
;         const bfr yb = f2bf(y);
	v_fmac_f32_e32 v130, v50, v71
	v_mul_f32_e32 v131, 0xbfb8aa3b, v130
	v_exp_f32_e32 v131, v131
	s_nop 0
	v_add_f32_e32 v131, 1.0, v131
	v_div_scale_f32 v132, s[54:55], v131, v131, v130
	v_rcp_f32_e32 v133, v132
	s_nop 0
	v_fma_f32 v134, -v132, v133, 1.0
	v_fmac_f32_e32 v133, v134, v133
	v_div_scale_f32 v134, vcc, v130, v131, v130
	v_mul_f32_e32 v135, v134, v133
	v_fma_f32 v136, -v132, v135, v134
	v_fmac_f32_e32 v135, v136, v133
	v_fma_f32 v132, -v132, v135, v134
	v_div_fmas_f32 v132, v132, v133, v135
	v_div_fixup_f32 v130, v132, v131, v130
	v_cvt_pk_bf16_f32 v103, v130, s0
	v_fma_f32 v130, v46, v69, v49
	v_fmac_f32_e32 v130, v47, v70
	v_fmac_f32_e32 v130, v48, v71
	v_fmac_f32_e32 v130, v50, v72
	v_mul_f32_e32 v131, 0xbfb8aa3b, v130
	v_exp_f32_e32 v131, v131
	s_nop 0
	v_add_f32_e32 v131, 1.0, v131
	v_div_scale_f32 v132, s[54:55], v131, v131, v130
	v_rcp_f32_e32 v133, v132
	s_nop 0
	v_fma_f32 v134, -v132, v133, 1.0
	v_fmac_f32_e32 v133, v134, v133
	v_div_scale_f32 v134, vcc, v130, v131, v130
	v_mul_f32_e32 v135, v134, v133
	v_fma_f32 v136, -v132, v135, v134
	v_fmac_f32_e32 v135, v136, v133
	v_fma_f32 v132, -v132, v135, v134
	v_div_fmas_f32 v132, v132, v133, v135
	v_div_fixup_f32 v130, v132, v131, v130
	v_cvt_pk_bf16_f32 v104, v130, s0
	v_fma_f32 v130, v46, v70, v49
	v_fmac_f32_e32 v130, v47, v71
	v_fmac_f32_e32 v130, v48, v72
	v_fmac_f32_e32 v130, v50, v73
	v_mul_f32_e32 v131, 0xbfb8aa3b, v130
	v_exp_f32_e32 v131, v131
	s_nop 0
	v_add_f32_e32 v131, 1.0, v131
	v_div_scale_f32 v132, s[54:55], v131, v131, v130
	v_rcp_f32_e32 v133, v132
	s_nop 0
	v_fma_f32 v134, -v132, v133, 1.0
	v_fmac_f32_e32 v133, v134, v133
	v_div_scale_f32 v134, vcc, v130, v131, v130
	v_mul_f32_e32 v135, v134, v133
	v_fma_f32 v136, -v132, v135, v134
	v_fmac_f32_e32 v135, v136, v133
	v_fma_f32 v132, -v132, v135, v134
	v_div_fmas_f32 v132, v132, v133, v135
	v_div_fixup_f32 v130, v132, v131, v130
	v_cvt_pk_bf16_f32 v105, v130, s0
	v_fma_f32 v130, v46, v71, v49
	v_fmac_f32_e32 v130, v47, v72
	v_fmac_f32_e32 v130, v48, v73
	v_fmac_f32_e32 v130, v50, v74
	v_mul_f32_e32 v131, 0xbfb8aa3b, v130
	v_exp_f32_e32 v131, v131
	s_nop 0
	v_add_f32_e32 v131, 1.0, v131
	v_div_scale_f32 v132, s[54:55], v131, v131, v130
	v_rcp_f32_e32 v133, v132
	s_nop 0
	v_fma_f32 v134, -v132, v133, 1.0
	v_fmac_f32_e32 v133, v134, v133
	v_div_scale_f32 v134, vcc, v130, v131, v130
	v_mul_f32_e32 v135, v134, v133
	v_fma_f32 v136, -v132, v135, v134
	v_fmac_f32_e32 v135, v136, v133
	v_fma_f32 v132, -v132, v135, v134
	v_div_fmas_f32 v132, v132, v133, v135
	v_div_fixup_f32 v130, v132, v131, v130
	v_cvt_pk_bf16_f32 v106, v130, s0
	v_fma_f32 v130, v46, v72, v49
	v_fmac_f32_e32 v130, v47, v73
	v_fmac_f32_e32 v130, v48, v74
	v_fmac_f32_e32 v130, v50, v75
	v_mul_f32_e32 v131, 0xbfb8aa3b, v130
	v_exp_f32_e32 v131, v131
	s_nop 0
	v_add_f32_e32 v131, 1.0, v131
	v_div_scale_f32 v132, s[54:55], v131, v131, v130
	v_rcp_f32_e32 v133, v132
	s_nop 0
	v_fma_f32 v134, -v132, v133, 1.0
	v_fmac_f32_e32 v133, v134, v133
	v_div_scale_f32 v134, vcc, v130, v131, v130
	v_mul_f32_e32 v135, v134, v133
	v_fma_f32 v136, -v132, v135, v134
	v_fmac_f32_e32 v135, v136, v133
	v_fma_f32 v132, -v132, v135, v134
	v_div_fmas_f32 v132, v132, v133, v135
	v_div_fixup_f32 v130, v132, v131, v130
	v_cvt_pk_bf16_f32 v107, v130, s0
	v_fma_f32 v130, v46, v73, v49
	v_fmac_f32_e32 v130, v47, v74
	v_fmac_f32_e32 v130, v48, v75
	v_fmac_f32_e32 v130, v50, v76
	v_mul_f32_e32 v131, 0xbfb8aa3b, v130
	v_exp_f32_e32 v131, v131
	s_nop 0
	v_add_f32_e32 v131, 1.0, v131
	v_div_scale_f32 v132, s[54:55], v131, v131, v130
	v_rcp_f32_e32 v133, v132
	s_nop 0
	v_fma_f32 v134, -v132, v133, 1.0
	v_fmac_f32_e32 v133, v134, v133
	v_div_scale_f32 v134, vcc, v130, v131, v130
	v_mul_f32_e32 v135, v134, v133
	v_fma_f32 v136, -v132, v135, v134
	v_fmac_f32_e32 v135, v136, v133
	v_fma_f32 v132, -v132, v135, v134
	v_div_fmas_f32 v132, v132, v133, v135
	v_div_fixup_f32 v130, v132, v131, v130
	v_cvt_pk_bf16_f32 v108, v130, s0
	v_fma_f32 v130, v46, v74, v49
	v_fmac_f32_e32 v130, v47, v75
	v_fmac_f32_e32 v130, v48, v76
	v_fmac_f32_e32 v130, v50, v77
	v_mul_f32_e32 v131, 0xbfb8aa3b, v130
	v_exp_f32_e32 v131, v131
	s_nop 0
	v_add_f32_e32 v131, 1.0, v131
	v_div_scale_f32 v132, s[54:55], v131, v131, v130
	v_rcp_f32_e32 v133, v132
	s_nop 0
	v_fma_f32 v134, -v132, v133, 1.0
	v_fmac_f32_e32 v133, v134, v133
	v_div_scale_f32 v134, vcc, v130, v131, v130
	v_mul_f32_e32 v135, v134, v133
	v_fma_f32 v136, -v132, v135, v134
	v_fmac_f32_e32 v135, v136, v133
	v_fma_f32 v132, -v132, v135, v134
	v_div_fmas_f32 v132, v132, v133, v135
	v_div_fixup_f32 v130, v132, v131, v130
	v_cvt_pk_bf16_f32 v109, v130, s0
	v_fma_f32 v130, v46, v75, v49
	v_fmac_f32_e32 v130, v47, v76
	v_fmac_f32_e32 v130, v48, v77
	v_fmac_f32_e32 v130, v50, v78
	v_mul_f32_e32 v131, 0xbfb8aa3b, v130
	v_exp_f32_e32 v131, v131
; DI bfr f2bf(float a) { return (bfr)(pk2(a, 0.f) & 0xffffu); }
; DI float bf2f(bfr x) { return __uint_as_float(((unsigned)x) << 16); }
; DI float siluf_(float x) { return x / (1.f + __expf(-x)); }
; DI void ssd_conv_phase(const Params& p, int ei, unsigned char* smem) {
;     ...
;       for (int k = 0; k < 32; ++k) {
;         const float r3 = bf2f(xraw[(tg0 + k) * 1024 + c]);
;         const float y = siluf_(bias + w0 * r0 + w1 * r1 + w2 * r2 + w3 * r3);
;         r0 = r1; r1 = r2; r2 = r3;
;         const bfr yb = f2bf(y);
;         if (slab >= 8) bct[(tg0 + k) * 512 + c - 512] = yb;
;         if (slab < 12) tile[lane * 136 + tq * 32 + k] = yb;
;       }
	s_nop 0
	v_add_f32_e32 v131, 1.0, v131
	v_div_scale_f32 v132, s[54:55], v131, v131, v130
	v_rcp_f32_e32 v133, v132
	s_nop 0
	v_fma_f32 v134, -v132, v133, 1.0
	v_fmac_f32_e32 v133, v134, v133
	v_div_scale_f32 v134, vcc, v130, v131, v130
	v_mul_f32_e32 v135, v134, v133
	v_fma_f32 v136, -v132, v135, v134
	v_fmac_f32_e32 v135, v136, v133
	v_fma_f32 v132, -v132, v135, v134
	v_div_fmas_f32 v132, v132, v133, v135
	v_div_fixup_f32 v130, v132, v131, v130
	v_cvt_pk_bf16_f32 v110, v130, s0
	v_fma_f32 v130, v46, v76, v49
	v_fmac_f32_e32 v130, v47, v77
	v_fmac_f32_e32 v130, v48, v78
	v_fmac_f32_e32 v130, v50, v79
	v_mul_f32_e32 v131, 0xbfb8aa3b, v130
	v_exp_f32_e32 v131, v131
	s_nop 0
	v_add_f32_e32 v131, 1.0, v131
	v_div_scale_f32 v132, s[54:55], v131, v131, v130
	v_rcp_f32_e32 v133, v132
	s_nop 0
	v_fma_f32 v134, -v132, v133, 1.0
	v_fmac_f32_e32 v133, v134, v133
	v_div_scale_f32 v134, vcc, v130, v131, v130
	v_mul_f32_e32 v135, v134, v133
	v_fma_f32 v136, -v132, v135, v134
	v_fmac_f32_e32 v135, v136, v133
	v_fma_f32 v132, -v132, v135, v134
	v_div_fmas_f32 v132, v132, v133, v135
	v_div_fixup_f32 v130, v132, v131, v130
	v_cvt_pk_bf16_f32 v111, v130, s0
	v_fma_f32 v130, v46, v77, v49
	v_fmac_f32_e32 v130, v47, v78
	v_fmac_f32_e32 v130, v48, v79
	v_fmac_f32_e32 v130, v50, v80
	v_mul_f32_e32 v131, 0xbfb8aa3b, v130
	v_exp_f32_e32 v131, v131
	s_nop 0
	v_add_f32_e32 v131, 1.0, v131
	v_div_scale_f32 v132, s[54:55], v131, v131, v130
	v_rcp_f32_e32 v133, v132
	s_nop 0
	v_fma_f32 v134, -v132, v133, 1.0
	v_fmac_f32_e32 v133, v134, v133
	v_div_scale_f32 v134, vcc, v130, v131, v130
	v_mul_f32_e32 v135, v134, v133
	v_fma_f32 v136, -v132, v135, v134
	v_fmac_f32_e32 v135, v136, v133
	v_fma_f32 v132, -v132, v135, v134
	v_div_fmas_f32 v132, v132, v133, v135
	v_div_fixup_f32 v130, v132, v131, v130
	v_cvt_pk_bf16_f32 v112, v130, s0
	v_fma_f32 v130, v46, v78, v49
	v_fmac_f32_e32 v130, v47, v79
	v_fmac_f32_e32 v130, v48, v80
	v_fmac_f32_e32 v130, v50, v81
	v_mul_f32_e32 v131, 0xbfb8aa3b, v130
	v_exp_f32_e32 v131, v131
	s_nop 0
	v_add_f32_e32 v131, 1.0, v131
	v_div_scale_f32 v132, s[54:55], v131, v131, v130
	v_rcp_f32_e32 v133, v132
	s_nop 0
	v_fma_f32 v134, -v132, v133, 1.0
	v_fmac_f32_e32 v133, v134, v133
	v_div_scale_f32 v134, vcc, v130, v131, v130
	v_mul_f32_e32 v135, v134, v133
	v_fma_f32 v136, -v132, v135, v134
	v_fmac_f32_e32 v135, v136, v133
	v_fma_f32 v132, -v132, v135, v134
	v_div_fmas_f32 v132, v132, v133, v135
	v_div_fixup_f32 v130, v132, v131, v130
	v_cvt_pk_bf16_f32 v113, v130, s0
	v_mov_b32_e32 v54, v79
	v_mov_b32_e32 v52, v80
	v_mov_b32_e32 v51, v81
	s_andn2_b64 vcc, exec, s[4:5]
	s_cbranch_vccnz .Lconv_nobct
	global_store_short v[60:61], v98, off
	global_store_short v[62:63], v99, off
	v_lshl_add_u64 v[60:61], v[60:61], 0, s[92:93]
	v_lshl_add_u64 v[62:63], v[62:63], 0, s[92:93]
	global_store_short v[60:61], v100, off
	global_store_short v[62:63], v101, off
	v_lshl_add_u64 v[60:61], v[60:61], 0, s[92:93]
	v_lshl_add_u64 v[62:63], v[62:63], 0, s[92:93]
	global_store_short v[60:61], v102, off
	global_store_short v[62:63], v103, off
	v_lshl_add_u64 v[60:61], v[60:61], 0, s[92:93]
	v_lshl_add_u64 v[62:63], v[62:63], 0, s[92:93]
	global_store_short v[60:61], v104, off
	global_store_short v[62:63], v105, off
	v_lshl_add_u64 v[60:61], v[60:61], 0, s[92:93]
	v_lshl_add_u64 v[62:63], v[62:63], 0, s[92:93]
	global_store_short v[60:61], v106, off
	global_store_short v[62:63], v107, off
	v_lshl_add_u64 v[60:61], v[60:61], 0, s[92:93]
	v_lshl_add_u64 v[62:63], v[62:63], 0, s[92:93]
	global_store_short v[60:61], v108, off
	global_store_short v[62:63], v109, off
	v_lshl_add_u64 v[60:61], v[60:61], 0, s[92:93]
	v_lshl_add_u64 v[62:63], v[62:63], 0, s[92:93]
	global_store_short v[60:61], v110, off
	global_store_short v[62:63], v111, off
	v_lshl_add_u64 v[60:61], v[60:61], 0, s[92:93]
	v_lshl_add_u64 v[62:63], v[62:63], 0, s[92:93]
	global_store_short v[60:61], v112, off
	global_store_short v[62:63], v113, off
	v_lshl_add_u64 v[60:61], v[60:61], 0, s[92:93]
	v_lshl_add_u64 v[62:63], v[62:63], 0, s[92:93]
.Lconv_nobct:
	s_andn2_b64 vcc, exec, s[24:25]
	s_cbranch_vccnz .Lconv_notile
	ds_write_b16 v64, v98
	ds_write_b16 v64, v99 offset:2
	ds_write_b16 v64, v100 offset:4
	ds_write_b16 v64, v101 offset:6
	ds_write_b16 v64, v102 offset:8
	ds_write_b16 v64, v103 offset:10
	ds_write_b16 v64, v104 offset:12
	ds_write_b16 v64, v105 offset:14
	ds_write_b16 v64, v106 offset:16
	ds_write_b16 v64, v107 offset:18
	ds_write_b16 v64, v108 offset:20
	ds_write_b16 v64, v109 offset:22
	ds_write_b16 v64, v110 offset:24
	ds_write_b16 v64, v111 offset:26
	ds_write_b16 v64, v112 offset:28
	ds_write_b16 v64, v113 offset:30
.Lconv_notile:
	v_add_u32_e32 v64, 32, v64
	s_add_i32 s34, s34, 1
	s_cmp_lg_u32 s34, 2
	s_cbranch_scc1 .Lconv_round
	s_not_b64 s[56:57], s[24:25]
	s_branch .LBB0_593

; #define MFMA32(a, b, c) __builtin_amdgcn_mfma_f32_32x32x16_bf16((a), (b), (c), 0, 0, 0)
; #define GLOADS(K0) { _Pragma("unroll") for (int i = 0; i < 8; ++i) ra[i] = *(const u32x4*)(Ap + (size_t)(32 * i) * lda + (K0)); \
;                      _Pragma("unroll") for (int i = 0; i < 4; ++i) rb[i] = *(const u32x4*)(Bp + (size_t)(32 * i) * ldb + (K0)); }
; DI void gemm_phase_(const GemmDesc& d, unsigned char* smem, const XMap& xm) {
;     ...
;     for (int kt = 0; kt < KT; ++kt) {
;       __syncthreads();
; #pragma unroll
;       for (int i = 0; i < 8; ++i) *(u32x4*)(sAq + (lrow + 32 * i) * GLD + lcc) = ra[i];
; #pragma unroll
;       for (int i = 0; i < 4; ++i) *(u32x4*)(sBq + (lrow + 32 * i) * GLD + lcc) = rb[i];
;       __syncthreads();
;       if (kt + 1 < KT) GLOADS((kt + 1) * 64);
;       __builtin_amdgcn_s_setprio(3);
; #pragma unroll
;       for (int ks = 0; ks < 4; ++ks) {
;         bf16x8 bq[2];
; #pragma unroll
;         for (int j = 0; j < 2; ++j) bq[j] = *(const bf16x8*)(sBq + (wn * 64 + j * 32 + l32) * GLD + ks * 16 + half * 8);
; #pragma unroll
;         for (int ih = 0; ih < 2; ++ih) {
;           bf16x8 af[2];
; #pragma unroll
;           for (int i = 0; i < 2; ++i) af[i] = *(const bf16x8*)(sAq + (wm * 128 + (ih * 2 + i) * 32 + l32) * GLD + ks * 16 + half * 8);
; #pragma unroll
;           for (int i = 0; i < 2; ++i)
; #pragma unroll
;             for (int j = 0; j < 2; ++j) acc[ih * 2 + i][j] = MFMA32(af[i], bq[j], acc[ih * 2 + i][j]);
;         }
;       }
;       __builtin_amdgcn_s_setprio(0);
;     }
.LBB0_615:
	s_add_i32 s2, s2, 1
	s_cmp_ge_i32 s2, s66
	s_barrier
	s_waitcnt vmcnt(0)
	ds_write_b128 v229, v[144:147]
	ds_write_b128 v229, v[140:143] offset:4608
	ds_write_b128 v229, v[168:171] offset:9216
	ds_write_b128 v229, v[164:167] offset:13824
	ds_write_b128 v229, v[160:163] offset:18432
	ds_write_b128 v229, v[156:159] offset:23040
	ds_write_b128 v229, v[136:139] offset:27648
	ds_write_b128 v229, v[148:151] offset:32256
	ds_write_b128 v229, v[132:135] offset:36864
	ds_write_b128 v229, v[128:131] offset:41472
	ds_write_b128 v229, v[152:155] offset:46080
	ds_write_b128 v229, v[172:175] offset:50688
	s_waitcnt lgkmcnt(0)
	s_barrier
	ds_read_b128 v[234:237], v231
	ds_read_b128 v[238:241], v230 offset:36864
	ds_read_b128 v[242:245], v230 offset:41472
	ds_read_b128 v[202:205], v231 offset:4608
	ds_read_b128 v[208:211], v231 offset:9216
	ds_read_b128 v[180:183], v232
	ds_read_b128 v[184:187], v230 offset:36896
	ds_read_b128 v[192:195], v230 offset:41504
	s_cbranch_scc1 .Lgemm_mfma_last
	s_lshl_b64 s[10:11], s[28:29], 1
	v_lshl_add_u64 v[128:129], v[198:199], 0, s[10:11]
	v_lshl_add_u64 v[130:131], s[8:9], 1, v[128:129]
	global_load_dwordx4 v[144:147], v[128:129], off
	global_load_dwordx4 v[140:143], v[130:131], off
	s_setprio 3
	s_waitcnt lgkmcnt(5)
	v_mfma_f32_32x32x16_bf16 v[112:127], v[234:237], v[238:241], v[112:127]
	v_mfma_f32_32x32x16_bf16 v[80:95], v[234:237], v[242:245], v[80:95]
	ds_read_b128 v[234:237], v231 offset:32
	v_lshl_add_u64 v[128:129], v[130:131], 0, s[34:35]
	v_lshl_add_u64 v[130:131], v[128:129], 0, s[34:35]
	global_load_dwordx4 v[168:171], v[128:129], off
	global_load_dwordx4 v[164:167], v[130:131], off
	s_waitcnt lgkmcnt(5)
	v_mfma_f32_32x32x16_bf16 v[96:111], v[202:205], v[238:241], v[96:111]
	v_mfma_f32_32x32x16_bf16 v[64:79], v[202:205], v[242:245], v[64:79]
	ds_read_b128 v[202:205], v231 offset:4640
	v_lshl_add_u64 v[128:129], v[130:131], 0, s[34:35]
	v_lshl_add_u64 v[130:131], v[128:129], 0, s[34:35]
	global_load_dwordx4 v[160:163], v[128:129], off
	global_load_dwordx4 v[156:159], v[130:131], off
	s_waitcnt lgkmcnt(5)
	v_mfma_f32_32x32x16_bf16 v[48:63], v[208:211], v[238:241], v[48:63]
	v_mfma_f32_32x32x16_bf16 v[16:31], v[208:211], v[242:245], v[16:31]
	ds_read_b128 v[208:211], v231 offset:9248
	v_lshl_add_u64 v[128:129], v[130:131], 0, s[34:35]
	global_load_dwordx4 v[136:139], v[128:129], off
	v_lshl_add_u64 v[128:129], v[128:129], 0, s[34:35]
	global_load_dwordx4 v[148:151], v[128:129], off
	s_waitcnt lgkmcnt(5)
	v_mfma_f32_32x32x16_bf16 v[32:47], v[180:183], v[238:241], v[32:47]
	v_mfma_f32_32x32x16_bf16 v[0:15], v[180:183], v[242:245], v[0:15]
	ds_read_b128 v[180:183], v232 offset:32
	v_lshl_add_u64 v[128:129], v[200:201], 0, s[10:11]
	v_lshl_add_u64 v[152:153], s[12:13], 1, v[128:129]
	global_load_dwordx4 v[132:135], v[128:129], off
	ds_read_b128 v[238:241], v230 offset:36928
	ds_read_b128 v[242:245], v230 offset:41536
	s_waitcnt lgkmcnt(5)
	v_mfma_f32_32x32x16_bf16 v[112:127], v[234:237], v[184:187], v[112:127]
	v_mfma_f32_32x32x16_bf16 v[80:95], v[234:237], v[192:195], v[80:95]
	ds_read_b128 v[234:237], v231 offset:64
	s_nop 0
	global_load_dwordx4 v[128:131], v[152:153], off
	v_lshl_add_u64 v[152:153], v[152:153], 0, s[74:75]
	v_lshl_add_u64 v[172:173], v[152:153], 0, s[74:75]
	s_waitcnt lgkmcnt(5)
	v_mfma_f32_32x32x16_bf16 v[96:111], v[202:205], v[184:187], v[96:111]
	v_mfma_f32_32x32x16_bf16 v[64:79], v[202:205], v[192:195], v[64:79]
	ds_read_b128 v[202:205], v231 offset:4672
	global_load_dwordx4 v[152:155], v[152:153], off
	s_nop 0
	global_load_dwordx4 v[172:175], v[172:173], off
	s_waitcnt lgkmcnt(5)
	v_mfma_f32_32x32x16_bf16 v[48:63], v[208:211], v[184:187], v[48:63]
	v_mfma_f32_32x32x16_bf16 v[16:31], v[208:211], v[192:195], v[16:31]
	ds_read_b128 v[208:211], v231 offset:9280
	s_waitcnt lgkmcnt(5)
	v_mfma_f32_32x32x16_bf16 v[32:47], v[180:183], v[184:187], v[32:47]
	v_mfma_f32_32x32x16_bf16 v[0:15], v[180:183], v[192:195], v[0:15]
	ds_read_b128 v[180:183], v232 offset:64
	ds_read_b128 v[184:187], v230 offset:36960
	ds_read_b128 v[192:195], v230 offset:41568
	s_waitcnt lgkmcnt(5)
	v_mfma_f32_32x32x16_bf16 v[112:127], v[234:237], v[238:241], v[112:127]
	v_mfma_f32_32x32x16_bf16 v[80:95], v[234:237], v[242:245], v[80:95]
	ds_read_b128 v[234:237], v231 offset:96
	s_waitcnt lgkmcnt(5)
	v_mfma_f32_32x32x16_bf16 v[96:111], v[202:205], v[238:241], v[96:111]
	v_mfma_f32_32x32x16_bf16 v[64:79], v[202:205], v[242:245], v[64:79]
	ds_read_b128 v[202:205], v231 offset:4704
	s_waitcnt lgkmcnt(5)
	v_mfma_f32_32x32x16_bf16 v[48:63], v[208:211], v[238:241], v[48:63]
	v_mfma_f32_32x32x16_bf16 v[16:31], v[208:211], v[242:245], v[16:31]
	ds_read_b128 v[208:211], v231 offset:9312
	s_waitcnt lgkmcnt(5)
	v_mfma_f32_32x32x16_bf16 v[32:47], v[180:183], v[238:241], v[32:47]
	v_mfma_f32_32x32x16_bf16 v[0:15], v[180:183], v[242:245], v[0:15]
	ds_read_b128 v[180:183], v232 offset:96
	s_waitcnt lgkmcnt(3)
	v_mfma_f32_32x32x16_bf16 v[112:127], v[234:237], v[184:187], v[112:127]
	v_mfma_f32_32x32x16_bf16 v[80:95], v[234:237], v[192:195], v[80:95]
	s_waitcnt lgkmcnt(2)
	v_mfma_f32_32x32x16_bf16 v[96:111], v[202:205], v[184:187], v[96:111]
	v_mfma_f32_32x32x16_bf16 v[64:79], v[202:205], v[192:195], v[64:79]
	s_waitcnt lgkmcnt(1)
	v_mfma_f32_32x32x16_bf16 v[48:63], v[208:211], v[184:187], v[48:63]
	v_mfma_f32_32x32x16_bf16 v[16:31], v[208:211], v[192:195], v[16:31]
	s_waitcnt lgkmcnt(0)
	v_mfma_f32_32x32x16_bf16 v[32:47], v[180:183], v[184:187], v[32:47]
	v_mfma_f32_32x32x16_bf16 v[0:15], v[180:183], v[192:195], v[0:15]
	s_setprio 0
	s_add_i32 s28, s28, 64
	s_branch .LBB0_615
; #define MFMA32(a, b, c) __builtin_amdgcn_mfma_f32_32x32x16_bf16((a), (b), (c), 0, 0, 0)
; DI void gemm_phase_(const GemmDesc& d, unsigned char* smem, const XMap& xm) {
;     ...
;       __builtin_amdgcn_s_setprio(3);
; #pragma unroll
;       for (int ks = 0; ks < 4; ++ks) {
;         bf16x8 bq[2];
; #pragma unroll
;         for (int j = 0; j < 2; ++j) bq[j] = *(const bf16x8*)(sBq + (wn * 64 + j * 32 + l32) * GLD + ks * 16 + half * 8);
; #pragma unroll
;         for (int ih = 0; ih < 2; ++ih) {
;           bf16x8 af[2];
; #pragma unroll
;           for (int i = 0; i < 2; ++i) af[i] = *(const bf16x8*)(sAq + (wm * 128 + (ih * 2 + i) * 32 + l32) * GLD + ks * 16 + half * 8);
; #pragma unroll
;           for (int i = 0; i < 2; ++i)
; #pragma unroll
;             for (int j = 0; j < 2; ++j) acc[ih * 2 + i][j] = MFMA32(af[i], bq[j], acc[ih * 2 + i][j]);
;         }
;       }
;       __builtin_amdgcn_s_setprio(0);
;     }
;     const int zc = z, mtc = mt, ntc = nt;
;     __syncthreads();
;     float* rsl = (float*)smem + 13824;
;     if (rpart) {
;       {
;         const float* pp = rpart + (size_t)(mtc * 256 + tid) * 16;
;         float sm = 0.f;
; #pragma unroll
;         for (int q = 0; q < 4; ++q) { const f32x4 v = *(const f32x4*)(pp + q * 4); sm += v[0]; sm += v[1]; sm += v[2]; sm += v[3]; }
;         rsl[tid] = rsqrtf(sm * (1.f / DM) + EPS);
;       }
;       __syncthreads();
.Lgemm_mfma_last:
	s_setprio 3
	s_waitcnt lgkmcnt(5)
	v_mfma_f32_32x32x16_bf16 v[112:127], v[234:237], v[238:241], v[112:127]
	v_mfma_f32_32x32x16_bf16 v[80:95], v[234:237], v[242:245], v[80:95]
	ds_read_b128 v[234:237], v231 offset:32
	s_waitcnt lgkmcnt(5)
	v_mfma_f32_32x32x16_bf16 v[96:111], v[202:205], v[238:241], v[96:111]
	v_mfma_f32_32x32x16_bf16 v[64:79], v[202:205], v[242:245], v[64:79]
	ds_read_b128 v[202:205], v231 offset:4640
	s_waitcnt lgkmcnt(5)
	v_mfma_f32_32x32x16_bf16 v[48:63], v[208:211], v[238:241], v[48:63]
	v_mfma_f32_32x32x16_bf16 v[16:31], v[208:211], v[242:245], v[16:31]
	ds_read_b128 v[208:211], v231 offset:9248
	s_waitcnt lgkmcnt(5)
	v_mfma_f32_32x32x16_bf16 v[32:47], v[180:183], v[238:241], v[32:47]
	v_mfma_f32_32x32x16_bf16 v[0:15], v[180:183], v[242:245], v[0:15]
	ds_read_b128 v[180:183], v232 offset:32
	ds_read_b128 v[238:241], v230 offset:36928
	ds_read_b128 v[242:245], v230 offset:41536
	s_waitcnt lgkmcnt(5)
	v_mfma_f32_32x32x16_bf16 v[112:127], v[234:237], v[184:187], v[112:127]
	v_mfma_f32_32x32x16_bf16 v[80:95], v[234:237], v[192:195], v[80:95]
	ds_read_b128 v[234:237], v231 offset:64
	s_waitcnt lgkmcnt(5)
	v_mfma_f32_32x32x16_bf16 v[96:111], v[202:205], v[184:187], v[96:111]
	v_mfma_f32_32x32x16_bf16 v[64:79], v[202:205], v[192:195], v[64:79]
	ds_read_b128 v[202:205], v231 offset:4672
	s_waitcnt lgkmcnt(5)
	v_mfma_f32_32x32x16_bf16 v[48:63], v[208:211], v[184:187], v[48:63]
	v_mfma_f32_32x32x16_bf16 v[16:31], v[208:211], v[192:195], v[16:31]
	ds_read_b128 v[208:211], v231 offset:9280
	s_waitcnt lgkmcnt(5)
	v_mfma_f32_32x32x16_bf16 v[32:47], v[180:183], v[184:187], v[32:47]
	v_mfma_f32_32x32x16_bf16 v[0:15], v[180:183], v[192:195], v[0:15]
	ds_read_b128 v[180:183], v232 offset:64
	ds_read_b128 v[184:187], v230 offset:36960
	ds_read_b128 v[192:195], v230 offset:41568
	s_waitcnt lgkmcnt(5)
	v_mfma_f32_32x32x16_bf16 v[112:127], v[234:237], v[238:241], v[112:127]
	v_mfma_f32_32x32x16_bf16 v[80:95], v[234:237], v[242:245], v[80:95]
	ds_read_b128 v[234:237], v231 offset:96
	s_waitcnt lgkmcnt(5)
	v_mfma_f32_32x32x16_bf16 v[96:111], v[202:205], v[238:241], v[96:111]
	v_mfma_f32_32x32x16_bf16 v[64:79], v[202:205], v[242:245], v[64:79]
	ds_read_b128 v[202:205], v231 offset:4704
	s_waitcnt lgkmcnt(5)
	v_mfma_f32_32x32x16_bf16 v[48:63], v[208:211], v[238:241], v[48:63]
	v_mfma_f32_32x32x16_bf16 v[16:31], v[208:211], v[242:245], v[16:31]
	ds_read_b128 v[208:211], v231 offset:9312
	s_waitcnt lgkmcnt(5)
	v_mfma_f32_32x32x16_bf16 v[32:47], v[180:183], v[238:241], v[32:47]
	v_mfma_f32_32x32x16_bf16 v[0:15], v[180:183], v[242:245], v[0:15]
	ds_read_b128 v[180:183], v232 offset:96
	s_waitcnt lgkmcnt(3)
	v_mfma_f32_32x32x16_bf16 v[112:127], v[234:237], v[184:187], v[112:127]
	v_mfma_f32_32x32x16_bf16 v[80:95], v[234:237], v[192:195], v[80:95]
	s_waitcnt lgkmcnt(2)
	v_mfma_f32_32x32x16_bf16 v[96:111], v[202:205], v[184:187], v[96:111]
	v_mfma_f32_32x32x16_bf16 v[64:79], v[202:205], v[192:195], v[64:79]
	s_waitcnt lgkmcnt(1)
	v_mfma_f32_32x32x16_bf16 v[48:63], v[208:211], v[184:187], v[48:63]
	v_mfma_f32_32x32x16_bf16 v[16:31], v[208:211], v[192:195], v[16:31]
	s_waitcnt lgkmcnt(0)
	v_mfma_f32_32x32x16_bf16 v[32:47], v[180:183], v[184:187], v[32:47]
	v_mfma_f32_32x32x16_bf16 v[0:15], v[180:183], v[192:195], v[0:15]
	s_setprio 0
.LBB0_617:
	v_lshlrev_b32_e32 v234, 2, v215
	v_add_u32_e32 v234, 0xde20, v234
	ds_read_b128 v[202:205], v234
	ds_read_b128 v[208:211], v234 offset:4096
	ds_read_b128 v[180:183], v234 offset:8192
	ds_read_b128 v[184:187], v234 offset:12288
	ds_read_b128 v[192:195], v234 offset:16384
	s_waitcnt lgkmcnt(0)
	s_and_b64 vcc, exec, s[0:1]
	s_barrier
	s_cbranch_vccz .LBB0_619
	s_waitcnt vmcnt(2)
	v_add_u32_e32 v128, s59, v179
	v_ashrrev_i32_e32 v129, 31, v128
	v_readlane_b32 s2, v249, 22
	v_lshlrev_b64 v[128:129], 6, v[128:129]
	v_readlane_b32 s3, v249, 23
	s_nop 1
	v_lshl_add_u64 v[140:141], s[2:3], 0, v[128:129]
	global_load_dwordx4 v[128:131], v[140:141], off
	global_load_dwordx4 v[132:135], v[140:141], off offset:16
	global_load_dwordx4 v[136:139], v[140:141], off offset:32
	s_nop 0
	global_load_dwordx4 v[140:143], v[140:141], off offset:48
	s_waitcnt vmcnt(3)
	v_add_f32_e32 v128, 0, v128
	v_add_f32_e32 v128, v129, v128
	v_add_f32_e32 v128, v130, v128
	v_add_f32_e32 v128, v131, v128
	s_waitcnt vmcnt(2)
	v_add_f32_e32 v128, v132, v128
	v_add_f32_e32 v128, v133, v128
	v_add_f32_e32 v128, v134, v128
	v_add_f32_e32 v128, v135, v128
	s_waitcnt vmcnt(1)
	v_add_f32_e32 v128, v136, v128
	v_add_f32_e32 v128, v137, v128
	v_add_f32_e32 v128, v138, v128
	v_add_f32_e32 v128, v139, v128
	s_waitcnt vmcnt(0)
	v_add_f32_e32 v128, v140, v128
	v_add_f32_e32 v128, v141, v128
	v_add_f32_e32 v128, v142, v128
	v_add_f32_e32 v128, v143, v128
	v_fmamk_f32 v128, v128, 0x3a800000, v193
	v_mul_f32_e32 v129, 0x4b800000, v128
	v_cmp_gt_f32_e32 vcc, s97, v128
	s_nop 1
	v_cndmask_b32_e32 v128, v128, v129, vcc
	v_rsq_f32_e32 v128, v128
	s_nop 0
	v_mul_f32_e32 v129, 0x45800000, v128
	v_cndmask_b32_e32 v128, v128, v129, vcc
	ds_write_b32 v215, v128 offset:55296
	s_waitcnt lgkmcnt(0)
	s_barrier
